# barrier: issue consumer-side buffer_inv sc1 at arrival (overlaps the wait) instead of after release
# speedup vs baseline: 1.0099x; 1.0099x over previous
; __device__ __forceinline__ unsigned xb_ld(unsigned* p)              { return __hip_atomic_load(p, __ATOMIC_RELAXED, __HIP_MEMORY_SCOPE_AGENT); }
; __device__ __forceinline__ unsigned xb_add(unsigned* p, unsigned v) { return __hip_atomic_fetch_add(p, v, __ATOMIC_RELAXED, __HIP_MEMORY_SCOPE_AGENT); }
; #define XB_SPIN(cond, bar) do { unsigned _sp = 0; while (cond) { __builtin_amdgcn_s_sleep(1); \
;     if ((++_sp & 255u) == 0u) { if (xb_ld(&(bar)[XB_TMO])) break; if (_sp > XB_SPIN_CAP) { atomicAdd(&(bar)[XB_TMO], 1u); break; } } } } while (0)
; __device__ __forceinline__ void xcd_barrier(const XcdBarrier& b) {
;     ...
;         const unsigned old = xb_add(&bar[XB_XSUB(b.x)], 1u);
;         const unsigned gen = old / nloc;
;         if (old + 1u == (gen + 1u) * nloc) {
;             __builtin_amdgcn_fence(__ATOMIC_RELEASE, "agent");
;             asm volatile("s_waitcnt vmcnt(0)" ::: "memory");
;             const unsigned og = xb_add(&bar[XB_TOP], 1u);
;             const unsigned tg = og / nx;
;             if (og + 1u == (tg + 1u) * nx) xb_add(&bar[XB_TOPGEN], 1u);
;             else XB_SPIN(xb_ld(&bar[XB_TOPGEN]) == tg, bar);
;             __builtin_amdgcn_fence(__ATOMIC_ACQUIRE, "agent");
;             xb_add(&bar[XB_XGEN(b.x)], 1u);
;             asm volatile("s_waitcnt vmcnt(0)" ::: "memory");
;         } else {
;             XB_SPIN(xb_ld(&bar[XB_XGEN(b.x)]) == gen, bar);
.LBB0_31:
	s_or_b64 exec, exec, s[10:11]
	v_cvt_f32_u32_e32 v5, v3
	s_waitcnt vmcnt(0)
	v_readfirstlane_b32 s8, v4
	v_sub_u32_e32 v4, 0, v3
	v_rcp_iflag_f32_e32 v5, v5
	v_add_u32_e32 v6, s8, v2
	v_mul_f32_e32 v5, 0x4f7ffffe, v5
	v_cvt_u32_f32_e32 v5, v5
	v_mul_lo_u32 v2, v4, v5
	v_mul_hi_u32 v2, v5, v2
	v_add_u32_e32 v2, v5, v2
	v_mul_hi_u32 v2, v6, v2
	v_mul_lo_u32 v4, v2, v3
	v_sub_u32_e32 v4, v6, v4
	v_add_u32_e32 v5, 1, v2
	v_cmp_ge_u32_e32 vcc, v4, v3
	s_nop 1
	v_cndmask_b32_e32 v2, v2, v5, vcc
	v_sub_u32_e32 v5, v4, v3
	v_cndmask_b32_e32 v4, v4, v5, vcc
	v_add_u32_e32 v5, 1, v2
	v_cmp_ge_u32_e32 vcc, v4, v3
	v_add_u32_e32 v4, 1, v6
	s_nop 0
	v_cndmask_b32_e32 v2, v2, v5, vcc
	v_mul_lo_u32 v5, v3, v2
	v_add_u32_e32 v3, v5, v3
	v_cmp_ne_u32_e32 vcc, v4, v3
	s_and_saveexec_b64 s[8:9], vcc
	s_xor_b64 s[8:9], exec, s[8:9]
	s_cbranch_execz .LBB0_45
	s_waitcnt lgkmcnt(0)
	buffer_inv sc1
	v_mov_b32_e32 v1, 0x2000
	global_load_dword v1, v1, s[6:7] offset:1024 sc1
	s_add_u32 s16, s6, 0x2400
	s_addc_u32 s17, s7, 0
	s_waitcnt vmcnt(0)
	v_cmp_eq_u32_e32 vcc, v1, v2
	s_and_saveexec_b64 s[10:11], vcc
	s_cbranch_execz .LBB0_44
	s_add_u32 s12, s60, 0x4200
	s_addc_u32 s13, s61, 0
	s_mov_b32 s14, 1
	s_mov_b64 s[18:19], 0
	v_mov_b32_e32 v1, 0
	s_branch .LBB0_35

; __device__ __forceinline__ unsigned xb_ld(unsigned* p)              { return __hip_atomic_load(p, __ATOMIC_RELAXED, __HIP_MEMORY_SCOPE_AGENT); }
; #define XB_SPIN(cond, bar) do { unsigned _sp = 0; while (cond) { __builtin_amdgcn_s_sleep(1); \
;     if ((++_sp & 255u) == 0u) { if (xb_ld(&(bar)[XB_TMO])) break; if (_sp > XB_SPIN_CAP) { atomicAdd(&(bar)[XB_TMO], 1u); break; } } } } while (0)
; __device__ __forceinline__ void xcd_barrier(const XcdBarrier& b) {
;     ...
;             XB_SPIN(xb_ld(&bar[XB_XGEN(b.x)]) == gen, bar);
;             __builtin_amdgcn_fence(__ATOMIC_ACQUIRE, "agent");
;             asm volatile("s_waitcnt vmcnt(0)" ::: "memory");
.LBB0_44:
	s_or_b64 exec, exec, s[10:11]
	s_waitcnt vmcnt(0)
	s_waitcnt vmcnt(0)

; __device__ __forceinline__ unsigned xb_ld(unsigned* p)              { return __hip_atomic_load(p, __ATOMIC_RELAXED, __HIP_MEMORY_SCOPE_AGENT); }
; __device__ __forceinline__ unsigned xb_add(unsigned* p, unsigned v) { return __hip_atomic_fetch_add(p, v, __ATOMIC_RELAXED, __HIP_MEMORY_SCOPE_AGENT); }
; #define XB_SPIN(cond, bar) do { unsigned _sp = 0; while (cond) { __builtin_amdgcn_s_sleep(1); \
;     if ((++_sp & 255u) == 0u) { if (xb_ld(&(bar)[XB_TMO])) break; if (_sp > XB_SPIN_CAP) { atomicAdd(&(bar)[XB_TMO], 1u); break; } } } } while (0)
; __device__ __forceinline__ void xcd_barrier(const XcdBarrier& b) {
;     ...
;             const unsigned og = xb_add(&bar[XB_TOP], 1u);
;             const unsigned tg = og / nx;
;             if (og + 1u == (tg + 1u) * nx) xb_add(&bar[XB_TOPGEN], 1u);
;             else XB_SPIN(xb_ld(&bar[XB_TOPGEN]) == tg, bar);
.LBB0_48:
	s_or_b64 exec, exec, s[10:11]
	v_cvt_f32_u32_e32 v4, v1
	s_waitcnt vmcnt(0)
	v_readfirstlane_b32 s8, v3
	buffer_inv sc1
	s_add_u32 s10, s60, 0x7500
	s_addc_u32 s11, s61, 0
	v_rcp_iflag_f32_e32 v4, v4
	v_add_u32_e32 v2, s8, v2
	v_add_u32_e32 v5, 1, v2
	s_mov_b64 s[12:13], -1
	v_mul_f32_e32 v3, 0x4f7ffffe, v4
	v_cvt_u32_f32_e32 v3, v3
	v_sub_u32_e32 v4, 0, v1
	v_mul_lo_u32 v4, v4, v3
	v_mul_hi_u32 v4, v3, v4
	v_add_u32_e32 v3, v3, v4
	v_mul_hi_u32 v3, v2, v3
	v_mul_lo_u32 v4, v3, v1
	v_sub_u32_e32 v2, v2, v4
	v_add_u32_e32 v6, 1, v3
	v_cmp_ge_u32_e32 vcc, v2, v1
	v_sub_u32_e32 v4, v2, v1
	s_nop 0
	v_cndmask_b32_e32 v3, v3, v6, vcc
	v_cndmask_b32_e32 v2, v2, v4, vcc
	v_add_u32_e32 v4, 1, v3
	v_cmp_ge_u32_e32 vcc, v2, v1
	s_nop 1
	v_cndmask_b32_e32 v4, v3, v4, vcc
	v_mul_lo_u32 v2, v1, v4
	v_add_u32_e32 v1, v2, v1
	v_cmp_ne_u32_e32 vcc, v5, v1
	v_mov_b64_e32 v[2:3], s[10:11]
	s_and_saveexec_b64 s[8:9], vcc
	s_cbranch_execz .LBB0_60
	v_mov_b32_e32 v1, 0
	global_load_dword v2, v1, s[10:11] sc1
	s_mov_b64 s[18:19], 0
	s_waitcnt vmcnt(0)
	v_cmp_eq_u32_e32 vcc, v2, v4
	s_and_saveexec_b64 s[16:17], vcc
	s_cbranch_execz .LBB0_59
	s_add_u32 s12, s60, 0x4200
	s_addc_u32 s13, s61, 0
	s_mov_b32 s14, 1
	s_branch .LBB0_52

; __device__ __forceinline__ unsigned xb_ld(unsigned* p)              { return __hip_atomic_load(p, __ATOMIC_RELAXED, __HIP_MEMORY_SCOPE_AGENT); }
; __device__ __forceinline__ unsigned xb_add(unsigned* p, unsigned v) { return __hip_atomic_fetch_add(p, v, __ATOMIC_RELAXED, __HIP_MEMORY_SCOPE_AGENT); }
; #define XB_SPIN(cond, bar) do { unsigned _sp = 0; while (cond) { __builtin_amdgcn_s_sleep(1); \
;     if ((++_sp & 255u) == 0u) { if (xb_ld(&(bar)[XB_TMO])) break; if (_sp > XB_SPIN_CAP) { atomicAdd(&(bar)[XB_TMO], 1u); break; } } } } while (0)
; __device__ __forceinline__ void xcd_barrier(const XcdBarrier& b) {
;     ...
;             else XB_SPIN(xb_ld(&bar[XB_TOPGEN]) == tg, bar);
;             __builtin_amdgcn_fence(__ATOMIC_ACQUIRE, "agent");
;             xb_add(&bar[XB_XGEN(b.x)], 1u);
;             asm volatile("s_waitcnt vmcnt(0)" ::: "memory");
.LBB0_62:
	s_or_b64 exec, exec, s[8:9]
	s_mov_b64 s[8:9], exec
	v_mbcnt_lo_u32_b32 v1, s8, 0
	v_mbcnt_hi_u32_b32 v1, s9, v1
	v_cmp_eq_u32_e32 vcc, 0, v1
	s_and_saveexec_b64 s[10:11], vcc
	s_cbranch_execz .LBB0_64
	s_bcnt1_i32_b64 s8, s[8:9]
	v_mov_b32_e32 v1, 0x2000
	v_mov_b32_e32 v2, s8
	global_atomic_add v1, v2, s[6:7] offset:1024

; __device__ __forceinline__ unsigned xb_ld(unsigned* p)              { return __hip_atomic_load(p, __ATOMIC_RELAXED, __HIP_MEMORY_SCOPE_AGENT); }
; __device__ __forceinline__ unsigned xb_add(unsigned* p, unsigned v) { return __hip_atomic_fetch_add(p, v, __ATOMIC_RELAXED, __HIP_MEMORY_SCOPE_AGENT); }
; #define XB_SPIN(cond, bar) do { unsigned _sp = 0; while (cond) { __builtin_amdgcn_s_sleep(1); \
;     if ((++_sp & 255u) == 0u) { if (xb_ld(&(bar)[XB_TMO])) break; if (_sp > XB_SPIN_CAP) { atomicAdd(&(bar)[XB_TMO], 1u); break; } } } } while (0)
; __device__ __forceinline__ void xcd_barrier(const XcdBarrier& b) {
;     ...
;         const unsigned old = xb_add(&bar[XB_XSUB(b.x)], 1u);
;         const unsigned gen = old / nloc;
;         if (old + 1u == (gen + 1u) * nloc) {
;             __builtin_amdgcn_fence(__ATOMIC_RELEASE, "agent");
;             asm volatile("s_waitcnt vmcnt(0)" ::: "memory");
;             const unsigned og = xb_add(&bar[XB_TOP], 1u);
;             const unsigned tg = og / nx;
;             if (og + 1u == (tg + 1u) * nx) xb_add(&bar[XB_TOPGEN], 1u);
;             else XB_SPIN(xb_ld(&bar[XB_TOPGEN]) == tg, bar);
;             __builtin_amdgcn_fence(__ATOMIC_ACQUIRE, "agent");
;             xb_add(&bar[XB_XGEN(b.x)], 1u);
;             asm volatile("s_waitcnt vmcnt(0)" ::: "memory");
;         } else {
;             XB_SPIN(xb_ld(&bar[XB_XGEN(b.x)]) == gen, bar);
.LBB0_119:
	s_or_b64 exec, exec, s[8:9]
	v_cvt_f32_u32_e32 v5, v3
	s_waitcnt vmcnt(0)
	v_readfirstlane_b32 s3, v4
	v_sub_u32_e32 v4, 0, v3
	v_rcp_iflag_f32_e32 v5, v5
	v_add_u32_e32 v6, s3, v2
	v_mul_f32_e32 v5, 0x4f7ffffe, v5
	v_cvt_u32_f32_e32 v5, v5
	v_mul_lo_u32 v2, v4, v5
	v_mul_hi_u32 v2, v5, v2
	v_add_u32_e32 v2, v5, v2
	v_mul_hi_u32 v2, v6, v2
	v_mul_lo_u32 v4, v2, v3
	v_sub_u32_e32 v4, v6, v4
	v_add_u32_e32 v5, 1, v2
	v_cmp_ge_u32_e32 vcc, v4, v3
	s_nop 1
	v_cndmask_b32_e32 v2, v2, v5, vcc
	v_sub_u32_e32 v5, v4, v3
	v_cndmask_b32_e32 v4, v4, v5, vcc
	v_add_u32_e32 v5, 1, v2
	v_cmp_ge_u32_e32 vcc, v4, v3
	v_add_u32_e32 v4, 1, v6
	s_nop 0
	v_cndmask_b32_e32 v2, v2, v5, vcc
	v_mul_lo_u32 v5, v3, v2
	v_add_u32_e32 v3, v5, v3
	v_cmp_ne_u32_e32 vcc, v4, v3
	s_and_saveexec_b64 s[6:7], vcc
	s_xor_b64 s[6:7], exec, s[6:7]
	s_cbranch_execz .LBB0_133
	s_waitcnt lgkmcnt(0)
	buffer_inv sc1
	v_mov_b32_e32 v1, 0x2000
	global_load_dword v1, v1, s[4:5] offset:1024 sc1
	s_add_u32 s12, s4, 0x2400
	s_addc_u32 s13, s5, 0
	s_waitcnt vmcnt(0)
	v_cmp_eq_u32_e32 vcc, v1, v2
	s_and_saveexec_b64 s[8:9], vcc
	s_cbranch_execz .LBB0_132
	s_add_u32 s10, s60, 0x4200
	s_addc_u32 s11, s61, 0
	s_mov_b32 s3, 1
	s_mov_b64 s[16:17], 0
	v_mov_b32_e32 v1, 0
	s_branch .LBB0_123

; __device__ __forceinline__ unsigned xb_ld(unsigned* p)              { return __hip_atomic_load(p, __ATOMIC_RELAXED, __HIP_MEMORY_SCOPE_AGENT); }
; #define XB_SPIN(cond, bar) do { unsigned _sp = 0; while (cond) { __builtin_amdgcn_s_sleep(1); \
;     if ((++_sp & 255u) == 0u) { if (xb_ld(&(bar)[XB_TMO])) break; if (_sp > XB_SPIN_CAP) { atomicAdd(&(bar)[XB_TMO], 1u); break; } } } } while (0)
; __device__ __forceinline__ void xcd_barrier(const XcdBarrier& b) {
;     ...
;             XB_SPIN(xb_ld(&bar[XB_XGEN(b.x)]) == gen, bar);
;             __builtin_amdgcn_fence(__ATOMIC_ACQUIRE, "agent");
;             asm volatile("s_waitcnt vmcnt(0)" ::: "memory");
.LBB0_132:
	s_or_b64 exec, exec, s[8:9]
	s_waitcnt vmcnt(0)
	s_waitcnt vmcnt(0)

; __device__ __forceinline__ unsigned xb_ld(unsigned* p)              { return __hip_atomic_load(p, __ATOMIC_RELAXED, __HIP_MEMORY_SCOPE_AGENT); }
; __device__ __forceinline__ unsigned xb_add(unsigned* p, unsigned v) { return __hip_atomic_fetch_add(p, v, __ATOMIC_RELAXED, __HIP_MEMORY_SCOPE_AGENT); }
; #define XB_SPIN(cond, bar) do { unsigned _sp = 0; while (cond) { __builtin_amdgcn_s_sleep(1); \
;     if ((++_sp & 255u) == 0u) { if (xb_ld(&(bar)[XB_TMO])) break; if (_sp > XB_SPIN_CAP) { atomicAdd(&(bar)[XB_TMO], 1u); break; } } } } while (0)
; __device__ __forceinline__ void xcd_barrier(const XcdBarrier& b) {
;     ...
;             const unsigned og = xb_add(&bar[XB_TOP], 1u);
;             const unsigned tg = og / nx;
;             if (og + 1u == (tg + 1u) * nx) xb_add(&bar[XB_TOPGEN], 1u);
;             else XB_SPIN(xb_ld(&bar[XB_TOPGEN]) == tg, bar);
.LBB0_136:
	s_or_b64 exec, exec, s[8:9]
	v_cvt_f32_u32_e32 v4, v1
	s_waitcnt vmcnt(0)
	v_readfirstlane_b32 s3, v3
	buffer_inv sc1
	s_add_u32 s8, s60, 0x7500
	s_addc_u32 s9, s61, 0
	v_rcp_iflag_f32_e32 v4, v4
	v_add_u32_e32 v2, s3, v2
	v_add_u32_e32 v5, 1, v2
	s_mov_b64 s[10:11], -1
	v_mul_f32_e32 v3, 0x4f7ffffe, v4
	v_cvt_u32_f32_e32 v3, v3
	v_sub_u32_e32 v4, 0, v1
	v_mul_lo_u32 v4, v4, v3
	v_mul_hi_u32 v4, v3, v4
	v_add_u32_e32 v3, v3, v4
	v_mul_hi_u32 v3, v2, v3
	v_mul_lo_u32 v4, v3, v1
	v_sub_u32_e32 v2, v2, v4
	v_add_u32_e32 v6, 1, v3
	v_cmp_ge_u32_e32 vcc, v2, v1
	v_sub_u32_e32 v4, v2, v1
	s_nop 0
	v_cndmask_b32_e32 v3, v3, v6, vcc
	v_cndmask_b32_e32 v2, v2, v4, vcc
	v_add_u32_e32 v4, 1, v3
	v_cmp_ge_u32_e32 vcc, v2, v1
	s_nop 1
	v_cndmask_b32_e32 v4, v3, v4, vcc
	v_mul_lo_u32 v2, v1, v4
	v_add_u32_e32 v1, v2, v1
	v_cmp_ne_u32_e32 vcc, v5, v1
	v_mov_b64_e32 v[2:3], s[8:9]
	s_and_saveexec_b64 s[6:7], vcc
	s_cbranch_execz .LBB0_148
	v_mov_b32_e32 v1, 0
	global_load_dword v2, v1, s[8:9] sc1
	s_mov_b64 s[16:17], 0
	s_waitcnt vmcnt(0)
	v_cmp_eq_u32_e32 vcc, v2, v4
	s_and_saveexec_b64 s[12:13], vcc
	s_cbranch_execz .LBB0_147
	s_add_u32 s10, s60, 0x4200
	s_addc_u32 s11, s61, 0
	s_mov_b32 s3, 1
	s_branch .LBB0_140

; __device__ __forceinline__ unsigned xb_ld(unsigned* p)              { return __hip_atomic_load(p, __ATOMIC_RELAXED, __HIP_MEMORY_SCOPE_AGENT); }
; __device__ __forceinline__ unsigned xb_add(unsigned* p, unsigned v) { return __hip_atomic_fetch_add(p, v, __ATOMIC_RELAXED, __HIP_MEMORY_SCOPE_AGENT); }
; #define XB_SPIN(cond, bar) do { unsigned _sp = 0; while (cond) { __builtin_amdgcn_s_sleep(1); \
;     if ((++_sp & 255u) == 0u) { if (xb_ld(&(bar)[XB_TMO])) break; if (_sp > XB_SPIN_CAP) { atomicAdd(&(bar)[XB_TMO], 1u); break; } } } } while (0)
; __device__ __forceinline__ void xcd_barrier(const XcdBarrier& b) {
;     ...
;             else XB_SPIN(xb_ld(&bar[XB_TOPGEN]) == tg, bar);
;             __builtin_amdgcn_fence(__ATOMIC_ACQUIRE, "agent");
;             xb_add(&bar[XB_XGEN(b.x)], 1u);
;             asm volatile("s_waitcnt vmcnt(0)" ::: "memory");
.LBB0_150:
	s_or_b64 exec, exec, s[6:7]
	s_mov_b64 s[6:7], exec
	v_mbcnt_lo_u32_b32 v1, s6, 0
	v_mbcnt_hi_u32_b32 v1, s7, v1
	v_cmp_eq_u32_e32 vcc, 0, v1
	s_and_saveexec_b64 s[8:9], vcc
	s_cbranch_execz .LBB0_152
	s_bcnt1_i32_b64 s3, s[6:7]
	v_mov_b32_e32 v1, 0x2000
	v_mov_b32_e32 v2, s3
	global_atomic_add v1, v2, s[4:5] offset:1024

; __device__ __forceinline__ unsigned xb_ld(unsigned* p)              { return __hip_atomic_load(p, __ATOMIC_RELAXED, __HIP_MEMORY_SCOPE_AGENT); }
; __device__ __forceinline__ unsigned xb_add(unsigned* p, unsigned v) { return __hip_atomic_fetch_add(p, v, __ATOMIC_RELAXED, __HIP_MEMORY_SCOPE_AGENT); }
; #define XB_SPIN(cond, bar) do { unsigned _sp = 0; while (cond) { __builtin_amdgcn_s_sleep(1); \
;     if ((++_sp & 255u) == 0u) { if (xb_ld(&(bar)[XB_TMO])) break; if (_sp > XB_SPIN_CAP) { atomicAdd(&(bar)[XB_TMO], 1u); break; } } } } while (0)
; __device__ __forceinline__ void xcd_barrier(const XcdBarrier& b) {
;     ...
;         const unsigned old = xb_add(&bar[XB_XSUB(b.x)], 1u);
;         const unsigned gen = old / nloc;
;         if (old + 1u == (gen + 1u) * nloc) {
;             __builtin_amdgcn_fence(__ATOMIC_RELEASE, "agent");
;             asm volatile("s_waitcnt vmcnt(0)" ::: "memory");
;             const unsigned og = xb_add(&bar[XB_TOP], 1u);
;             const unsigned tg = og / nx;
;             if (og + 1u == (tg + 1u) * nx) xb_add(&bar[XB_TOPGEN], 1u);
;             else XB_SPIN(xb_ld(&bar[XB_TOPGEN]) == tg, bar);
;             __builtin_amdgcn_fence(__ATOMIC_ACQUIRE, "agent");
;             xb_add(&bar[XB_XGEN(b.x)], 1u);
;             asm volatile("s_waitcnt vmcnt(0)" ::: "memory");
;         } else {
;             XB_SPIN(xb_ld(&bar[XB_XGEN(b.x)]) == gen, bar);
.LBB0_191:
	s_or_b64 exec, exec, s[6:7]
	v_cvt_f32_u32_e32 v5, v3
	s_waitcnt vmcnt(0)
	v_readfirstlane_b32 s4, v4
	v_sub_u32_e32 v4, 0, v3
	v_rcp_iflag_f32_e32 v5, v5
	v_add_u32_e32 v6, s4, v2
	v_mul_f32_e32 v5, 0x4f7ffffe, v5
	v_cvt_u32_f32_e32 v5, v5
	v_mul_lo_u32 v2, v4, v5
	v_mul_hi_u32 v2, v5, v2
	v_add_u32_e32 v2, v5, v2
	v_mul_hi_u32 v2, v6, v2
	v_mul_lo_u32 v4, v2, v3
	v_sub_u32_e32 v4, v6, v4
	v_add_u32_e32 v5, 1, v2
	v_cmp_ge_u32_e32 vcc, v4, v3
	s_nop 1
	v_cndmask_b32_e32 v2, v2, v5, vcc
	v_sub_u32_e32 v5, v4, v3
	v_cndmask_b32_e32 v4, v4, v5, vcc
	v_add_u32_e32 v5, 1, v2
	v_cmp_ge_u32_e32 vcc, v4, v3
	v_add_u32_e32 v4, 1, v6
	s_nop 0
	v_cndmask_b32_e32 v2, v2, v5, vcc
	v_mul_lo_u32 v5, v3, v2
	v_add_u32_e32 v3, v5, v3
	v_cmp_ne_u32_e32 vcc, v4, v3
	s_and_saveexec_b64 s[4:5], vcc
	s_xor_b64 s[4:5], exec, s[4:5]
	s_cbranch_execz .LBB0_205
	s_waitcnt lgkmcnt(0)
	buffer_inv sc1
	v_mov_b32_e32 v1, 0x2000
	global_load_dword v1, v1, s[2:3] offset:1024 sc1
	s_add_u32 s8, s2, 0x2400
	s_addc_u32 s9, s3, 0
	s_waitcnt vmcnt(0)
	v_cmp_eq_u32_e32 vcc, v1, v2
	s_and_saveexec_b64 s[6:7], vcc
	s_cbranch_execz .LBB0_204
	s_mov_b32 s14, 1
	s_mov_b64 s[10:11], 0
	v_mov_b32_e32 v1, 0
	s_branch .LBB0_195

; __device__ __forceinline__ unsigned xb_ld(unsigned* p)              { return __hip_atomic_load(p, __ATOMIC_RELAXED, __HIP_MEMORY_SCOPE_AGENT); }
; #define XB_SPIN(cond, bar) do { unsigned _sp = 0; while (cond) { __builtin_amdgcn_s_sleep(1); \
;     if ((++_sp & 255u) == 0u) { if (xb_ld(&(bar)[XB_TMO])) break; if (_sp > XB_SPIN_CAP) { atomicAdd(&(bar)[XB_TMO], 1u); break; } } } } while (0)
; __device__ __forceinline__ void xcd_barrier(const XcdBarrier& b) {
;     ...
;             XB_SPIN(xb_ld(&bar[XB_XGEN(b.x)]) == gen, bar);
;             __builtin_amdgcn_fence(__ATOMIC_ACQUIRE, "agent");
;             asm volatile("s_waitcnt vmcnt(0)" ::: "memory");
.LBB0_204:
	s_or_b64 exec, exec, s[6:7]
	s_waitcnt vmcnt(0)
	s_waitcnt vmcnt(0)

; __device__ __forceinline__ unsigned xb_ld(unsigned* p)              { return __hip_atomic_load(p, __ATOMIC_RELAXED, __HIP_MEMORY_SCOPE_AGENT); }
; __device__ __forceinline__ unsigned xb_add(unsigned* p, unsigned v) { return __hip_atomic_fetch_add(p, v, __ATOMIC_RELAXED, __HIP_MEMORY_SCOPE_AGENT); }
; #define XB_SPIN(cond, bar) do { unsigned _sp = 0; while (cond) { __builtin_amdgcn_s_sleep(1); \
;     if ((++_sp & 255u) == 0u) { if (xb_ld(&(bar)[XB_TMO])) break; if (_sp > XB_SPIN_CAP) { atomicAdd(&(bar)[XB_TMO], 1u); break; } } } } while (0)
; __device__ __forceinline__ void xcd_barrier(const XcdBarrier& b) {
;     ...
;             const unsigned og = xb_add(&bar[XB_TOP], 1u);
;             const unsigned tg = og / nx;
;             if (og + 1u == (tg + 1u) * nx) xb_add(&bar[XB_TOPGEN], 1u);
;             else XB_SPIN(xb_ld(&bar[XB_TOPGEN]) == tg, bar);
.LBB0_208:
	s_or_b64 exec, exec, s[8:9]
	v_cvt_f32_u32_e32 v4, v1
	s_waitcnt vmcnt(0)
	v_readfirstlane_b32 s6, v3
	buffer_inv sc1
	s_add_u32 s8, s34, 0x3500
	s_addc_u32 s9, s35, 0
	v_rcp_iflag_f32_e32 v4, v4
	v_add_u32_e32 v2, s6, v2
	v_add_u32_e32 v5, 1, v2
	s_mov_b64 s[10:11], -1
	v_mul_f32_e32 v3, 0x4f7ffffe, v4
	v_cvt_u32_f32_e32 v3, v3
	v_sub_u32_e32 v4, 0, v1
	v_mul_lo_u32 v4, v4, v3
	v_mul_hi_u32 v4, v3, v4
	v_add_u32_e32 v3, v3, v4
	v_mul_hi_u32 v3, v2, v3
	v_mul_lo_u32 v4, v3, v1
	v_sub_u32_e32 v2, v2, v4
	v_add_u32_e32 v6, 1, v3
	v_cmp_ge_u32_e32 vcc, v2, v1
	v_sub_u32_e32 v4, v2, v1
	s_nop 0
	v_cndmask_b32_e32 v3, v3, v6, vcc
	v_cndmask_b32_e32 v2, v2, v4, vcc
	v_add_u32_e32 v4, 1, v3
	v_cmp_ge_u32_e32 vcc, v2, v1
	s_nop 1
	v_cndmask_b32_e32 v4, v3, v4, vcc
	v_mul_lo_u32 v2, v1, v4
	v_add_u32_e32 v1, v2, v1
	v_cmp_ne_u32_e32 vcc, v5, v1
	v_mov_b64_e32 v[2:3], s[8:9]
	s_and_saveexec_b64 s[6:7], vcc
	s_cbranch_execz .LBB0_220
	v_mov_b32_e32 v1, 0
	global_load_dword v2, v1, s[8:9] sc1
	s_mov_b64 s[26:27], 0
	s_waitcnt vmcnt(0)
	v_cmp_eq_u32_e32 vcc, v2, v4
	s_and_saveexec_b64 s[12:13], vcc
	s_cbranch_execz .LBB0_219
	s_add_u32 s10, s34, 0x200
	s_addc_u32 s11, s35, 0
	s_mov_b32 s14, 1
	s_branch .LBB0_212

; __device__ __forceinline__ unsigned xb_ld(unsigned* p)              { return __hip_atomic_load(p, __ATOMIC_RELAXED, __HIP_MEMORY_SCOPE_AGENT); }
; __device__ __forceinline__ unsigned xb_add(unsigned* p, unsigned v) { return __hip_atomic_fetch_add(p, v, __ATOMIC_RELAXED, __HIP_MEMORY_SCOPE_AGENT); }
; #define XB_SPIN(cond, bar) do { unsigned _sp = 0; while (cond) { __builtin_amdgcn_s_sleep(1); \
;     if ((++_sp & 255u) == 0u) { if (xb_ld(&(bar)[XB_TMO])) break; if (_sp > XB_SPIN_CAP) { atomicAdd(&(bar)[XB_TMO], 1u); break; } } } } while (0)
; __device__ __forceinline__ void xcd_barrier(const XcdBarrier& b) {
;     ...
;             else XB_SPIN(xb_ld(&bar[XB_TOPGEN]) == tg, bar);
;             __builtin_amdgcn_fence(__ATOMIC_ACQUIRE, "agent");
;             xb_add(&bar[XB_XGEN(b.x)], 1u);
;             asm volatile("s_waitcnt vmcnt(0)" ::: "memory");
.LBB0_222:
	s_or_b64 exec, exec, s[6:7]
	s_mov_b64 s[6:7], exec
	v_mbcnt_lo_u32_b32 v1, s6, 0
	v_mbcnt_hi_u32_b32 v1, s7, v1
	v_cmp_eq_u32_e32 vcc, 0, v1
	s_and_saveexec_b64 s[8:9], vcc
	s_cbranch_execz .LBB0_224
	s_bcnt1_i32_b64 s6, s[6:7]
	v_mov_b32_e32 v1, 0x2000
	v_mov_b32_e32 v2, s6
	global_atomic_add v1, v2, s[2:3] offset:1024

; __device__ __forceinline__ unsigned xb_ld(unsigned* p)              { return __hip_atomic_load(p, __ATOMIC_RELAXED, __HIP_MEMORY_SCOPE_AGENT); }
; __device__ __forceinline__ unsigned xb_add(unsigned* p, unsigned v) { return __hip_atomic_fetch_add(p, v, __ATOMIC_RELAXED, __HIP_MEMORY_SCOPE_AGENT); }
; #define XB_SPIN(cond, bar) do { unsigned _sp = 0; while (cond) { __builtin_amdgcn_s_sleep(1); \
;     if ((++_sp & 255u) == 0u) { if (xb_ld(&(bar)[XB_TMO])) break; if (_sp > XB_SPIN_CAP) { atomicAdd(&(bar)[XB_TMO], 1u); break; } } } } while (0)
; __device__ __forceinline__ void xcd_barrier(const XcdBarrier& b) {
;     ...
;         const unsigned old = xb_add(&bar[XB_XSUB(b.x)], 1u);
;         const unsigned gen = old / nloc;
;         if (old + 1u == (gen + 1u) * nloc) {
;             __builtin_amdgcn_fence(__ATOMIC_RELEASE, "agent");
;             asm volatile("s_waitcnt vmcnt(0)" ::: "memory");
;             const unsigned og = xb_add(&bar[XB_TOP], 1u);
;             const unsigned tg = og / nx;
;             if (og + 1u == (tg + 1u) * nx) xb_add(&bar[XB_TOPGEN], 1u);
;             else XB_SPIN(xb_ld(&bar[XB_TOPGEN]) == tg, bar);
;             __builtin_amdgcn_fence(__ATOMIC_ACQUIRE, "agent");
;             xb_add(&bar[XB_XGEN(b.x)], 1u);
;             asm volatile("s_waitcnt vmcnt(0)" ::: "memory");
;         } else {
;             XB_SPIN(xb_ld(&bar[XB_XGEN(b.x)]) == gen, bar);
.LBB0_401:
	s_or_b64 exec, exec, s[8:9]
	v_cvt_f32_u32_e32 v5, v3
	s_waitcnt vmcnt(0)
	v_readfirstlane_b32 s6, v4
	v_sub_u32_e32 v4, 0, v3
	v_rcp_iflag_f32_e32 v5, v5
	v_add_u32_e32 v6, s6, v2
	v_mul_f32_e32 v5, 0x4f7ffffe, v5
	v_cvt_u32_f32_e32 v5, v5
	v_mul_lo_u32 v2, v4, v5
	v_mul_hi_u32 v2, v5, v2
	v_add_u32_e32 v2, v5, v2
	v_mul_hi_u32 v2, v6, v2
	v_mul_lo_u32 v4, v2, v3
	v_sub_u32_e32 v4, v6, v4
	v_add_u32_e32 v5, 1, v2
	v_cmp_ge_u32_e32 vcc, v4, v3
	s_nop 1
	v_cndmask_b32_e32 v2, v2, v5, vcc
	v_sub_u32_e32 v5, v4, v3
	v_cndmask_b32_e32 v4, v4, v5, vcc
	v_add_u32_e32 v5, 1, v2
	v_cmp_ge_u32_e32 vcc, v4, v3
	v_add_u32_e32 v4, 1, v6
	s_nop 0
	v_cndmask_b32_e32 v2, v2, v5, vcc
	v_mul_lo_u32 v5, v3, v2
	v_add_u32_e32 v3, v5, v3
	v_cmp_ne_u32_e32 vcc, v4, v3
	s_and_saveexec_b64 s[6:7], vcc
	s_xor_b64 s[6:7], exec, s[6:7]
	s_cbranch_execz .LBB0_415
	s_waitcnt lgkmcnt(0)
	buffer_inv sc1
	v_mov_b32_e32 v1, 0x2000
	global_load_dword v1, v1, s[4:5] offset:1024 sc1
	s_add_u32 s10, s4, 0x2400
	s_addc_u32 s11, s5, 0
	s_waitcnt vmcnt(0)
	v_cmp_eq_u32_e32 vcc, v1, v2
	s_and_saveexec_b64 s[8:9], vcc
	s_cbranch_execz .LBB0_414
	s_mov_b32 s14, 1
	s_mov_b64 s[12:13], 0
	v_mov_b32_e32 v1, 0
	s_branch .LBB0_405

; __device__ __forceinline__ unsigned xb_ld(unsigned* p)              { return __hip_atomic_load(p, __ATOMIC_RELAXED, __HIP_MEMORY_SCOPE_AGENT); }
; __device__ __forceinline__ unsigned xb_add(unsigned* p, unsigned v) { return __hip_atomic_fetch_add(p, v, __ATOMIC_RELAXED, __HIP_MEMORY_SCOPE_AGENT); }
; #define XB_SPIN(cond, bar) do { unsigned _sp = 0; while (cond) { __builtin_amdgcn_s_sleep(1); \
;     if ((++_sp & 255u) == 0u) { if (xb_ld(&(bar)[XB_TMO])) break; if (_sp > XB_SPIN_CAP) { atomicAdd(&(bar)[XB_TMO], 1u); break; } } } } while (0)
; __device__ __forceinline__ void xcd_barrier(const XcdBarrier& b) {
;     ...
;             const unsigned og = xb_add(&bar[XB_TOP], 1u);
;             const unsigned tg = og / nx;
;             if (og + 1u == (tg + 1u) * nx) xb_add(&bar[XB_TOPGEN], 1u);
;             else XB_SPIN(xb_ld(&bar[XB_TOPGEN]) == tg, bar);
.LBB0_418:
	s_or_b64 exec, exec, s[8:9]
	v_cvt_f32_u32_e32 v4, v1
	s_waitcnt vmcnt(0)
	v_readfirstlane_b32 s6, v3
	buffer_inv sc1
	s_add_u32 s8, s34, 0x3500
	s_addc_u32 s9, s35, 0
	v_rcp_iflag_f32_e32 v4, v4
	v_add_u32_e32 v2, s6, v2
	v_add_u32_e32 v5, 1, v2
	s_mov_b64 s[10:11], -1
	v_mul_f32_e32 v3, 0x4f7ffffe, v4
	v_cvt_u32_f32_e32 v3, v3
	v_sub_u32_e32 v4, 0, v1
	v_mul_lo_u32 v4, v4, v3
	v_mul_hi_u32 v4, v3, v4
	v_add_u32_e32 v3, v3, v4
	v_mul_hi_u32 v3, v2, v3
	v_mul_lo_u32 v4, v3, v1
	v_sub_u32_e32 v2, v2, v4
	v_add_u32_e32 v6, 1, v3
	v_cmp_ge_u32_e32 vcc, v2, v1
	v_sub_u32_e32 v4, v2, v1
	s_nop 0
	v_cndmask_b32_e32 v3, v3, v6, vcc
	v_cndmask_b32_e32 v2, v2, v4, vcc
	v_add_u32_e32 v4, 1, v3
	v_cmp_ge_u32_e32 vcc, v2, v1
	s_nop 1
	v_cndmask_b32_e32 v4, v3, v4, vcc
	v_mul_lo_u32 v2, v1, v4
	v_add_u32_e32 v1, v2, v1
	v_cmp_ne_u32_e32 vcc, v5, v1
	v_mov_b64_e32 v[2:3], s[8:9]
	s_and_saveexec_b64 s[6:7], vcc
	s_cbranch_execz .LBB0_430
	v_mov_b32_e32 v1, 0
	global_load_dword v2, v1, s[8:9] sc1
	s_mov_b64 s[18:19], 0
	s_waitcnt vmcnt(0)
	v_cmp_eq_u32_e32 vcc, v2, v4
	s_and_saveexec_b64 s[12:13], vcc
	s_cbranch_execz .LBB0_429
	s_add_u32 s10, s34, 0x200
	s_addc_u32 s11, s35, 0
	s_mov_b32 s14, 1
	s_branch .LBB0_422

; __device__ __forceinline__ unsigned xb_ld(unsigned* p)              { return __hip_atomic_load(p, __ATOMIC_RELAXED, __HIP_MEMORY_SCOPE_AGENT); }
; __device__ __forceinline__ unsigned xb_add(unsigned* p, unsigned v) { return __hip_atomic_fetch_add(p, v, __ATOMIC_RELAXED, __HIP_MEMORY_SCOPE_AGENT); }
; #define XB_SPIN(cond, bar) do { unsigned _sp = 0; while (cond) { __builtin_amdgcn_s_sleep(1); \
;     if ((++_sp & 255u) == 0u) { if (xb_ld(&(bar)[XB_TMO])) break; if (_sp > XB_SPIN_CAP) { atomicAdd(&(bar)[XB_TMO], 1u); break; } } } } while (0)
; __device__ __forceinline__ void xcd_barrier(const XcdBarrier& b) {
;     ...
;             else XB_SPIN(xb_ld(&bar[XB_TOPGEN]) == tg, bar);
;             __builtin_amdgcn_fence(__ATOMIC_ACQUIRE, "agent");
;             xb_add(&bar[XB_XGEN(b.x)], 1u);
;             asm volatile("s_waitcnt vmcnt(0)" ::: "memory");
.LBB0_432:
	s_or_b64 exec, exec, s[6:7]
	s_mov_b64 s[6:7], exec
	v_mbcnt_lo_u32_b32 v1, s6, 0
	v_mbcnt_hi_u32_b32 v1, s7, v1
	v_cmp_eq_u32_e32 vcc, 0, v1
	s_and_saveexec_b64 s[8:9], vcc
	s_cbranch_execz .LBB0_434
	s_bcnt1_i32_b64 s6, s[6:7]
	v_mov_b32_e32 v1, 0x2000
	v_mov_b32_e32 v2, s6
	global_atomic_add v1, v2, s[4:5] offset:1024

; __device__ __forceinline__ unsigned xb_ld(unsigned* p)              { return __hip_atomic_load(p, __ATOMIC_RELAXED, __HIP_MEMORY_SCOPE_AGENT); }
; __device__ __forceinline__ unsigned xb_add(unsigned* p, unsigned v) { return __hip_atomic_fetch_add(p, v, __ATOMIC_RELAXED, __HIP_MEMORY_SCOPE_AGENT); }
; #define XB_SPIN(cond, bar) do { unsigned _sp = 0; while (cond) { __builtin_amdgcn_s_sleep(1); \
;     if ((++_sp & 255u) == 0u) { if (xb_ld(&(bar)[XB_TMO])) break; if (_sp > XB_SPIN_CAP) { atomicAdd(&(bar)[XB_TMO], 1u); break; } } } } while (0)
; __device__ __forceinline__ void xcd_barrier(const XcdBarrier& b) {
;     ...
;         const unsigned old = xb_add(&bar[XB_XSUB(b.x)], 1u);
;         const unsigned gen = old / nloc;
;         if (old + 1u == (gen + 1u) * nloc) {
;             __builtin_amdgcn_fence(__ATOMIC_RELEASE, "agent");
;             asm volatile("s_waitcnt vmcnt(0)" ::: "memory");
;             const unsigned og = xb_add(&bar[XB_TOP], 1u);
;             const unsigned tg = og / nx;
;             if (og + 1u == (tg + 1u) * nx) xb_add(&bar[XB_TOPGEN], 1u);
;             else XB_SPIN(xb_ld(&bar[XB_TOPGEN]) == tg, bar);
;             __builtin_amdgcn_fence(__ATOMIC_ACQUIRE, "agent");
;             xb_add(&bar[XB_XGEN(b.x)], 1u);
;             asm volatile("s_waitcnt vmcnt(0)" ::: "memory");
;         } else {
;             XB_SPIN(xb_ld(&bar[XB_XGEN(b.x)]) == gen, bar);
.LBB0_475:
	s_or_b64 exec, exec, s[6:7]
	v_cvt_f32_u32_e32 v5, v3
	s_waitcnt vmcnt(0)
	v_readfirstlane_b32 s4, v4
	v_sub_u32_e32 v4, 0, v3
	v_rcp_iflag_f32_e32 v5, v5
	v_add_u32_e32 v6, s4, v2
	v_mul_f32_e32 v5, 0x4f7ffffe, v5
	v_cvt_u32_f32_e32 v5, v5
	v_mul_lo_u32 v2, v4, v5
	v_mul_hi_u32 v2, v5, v2
	v_add_u32_e32 v2, v5, v2
	v_mul_hi_u32 v2, v6, v2
	v_mul_lo_u32 v4, v2, v3
	v_sub_u32_e32 v4, v6, v4
	v_add_u32_e32 v5, 1, v2
	v_cmp_ge_u32_e32 vcc, v4, v3
	s_nop 1
	v_cndmask_b32_e32 v2, v2, v5, vcc
	v_sub_u32_e32 v5, v4, v3
	v_cndmask_b32_e32 v4, v4, v5, vcc
	v_add_u32_e32 v5, 1, v2
	v_cmp_ge_u32_e32 vcc, v4, v3
	v_add_u32_e32 v4, 1, v6
	s_nop 0
	v_cndmask_b32_e32 v2, v2, v5, vcc
	v_mul_lo_u32 v5, v3, v2
	v_add_u32_e32 v3, v5, v3
	v_cmp_ne_u32_e32 vcc, v4, v3
	s_and_saveexec_b64 s[4:5], vcc
	s_xor_b64 s[4:5], exec, s[4:5]
	s_cbranch_execz .LBB0_489
	s_waitcnt lgkmcnt(0)
	buffer_inv sc1
	v_mov_b32_e32 v1, 0x2000
	global_load_dword v1, v1, s[2:3] offset:1024 sc1
	s_add_u32 s8, s2, 0x2400
	s_addc_u32 s9, s3, 0
	s_waitcnt vmcnt(0)
	v_cmp_eq_u32_e32 vcc, v1, v2
	s_and_saveexec_b64 s[6:7], vcc
	s_cbranch_execz .LBB0_488
	s_mov_b32 s11, 1
	s_mov_b64 s[22:23], 0
	v_mov_b32_e32 v1, 0
	s_branch .LBB0_479

; __device__ __forceinline__ unsigned xb_ld(unsigned* p)              { return __hip_atomic_load(p, __ATOMIC_RELAXED, __HIP_MEMORY_SCOPE_AGENT); }
; __device__ __forceinline__ unsigned xb_add(unsigned* p, unsigned v) { return __hip_atomic_fetch_add(p, v, __ATOMIC_RELAXED, __HIP_MEMORY_SCOPE_AGENT); }
; #define XB_SPIN(cond, bar) do { unsigned _sp = 0; while (cond) { __builtin_amdgcn_s_sleep(1); \
;     if ((++_sp & 255u) == 0u) { if (xb_ld(&(bar)[XB_TMO])) break; if (_sp > XB_SPIN_CAP) { atomicAdd(&(bar)[XB_TMO], 1u); break; } } } } while (0)
; __device__ __forceinline__ void xcd_barrier(const XcdBarrier& b) {
;     ...
;             const unsigned og = xb_add(&bar[XB_TOP], 1u);
;             const unsigned tg = og / nx;
;             if (og + 1u == (tg + 1u) * nx) xb_add(&bar[XB_TOPGEN], 1u);
;             else XB_SPIN(xb_ld(&bar[XB_TOPGEN]) == tg, bar);
.LBB0_492:
	s_or_b64 exec, exec, s[8:9]
	v_cvt_f32_u32_e32 v4, v1
	s_waitcnt vmcnt(0)
	v_readfirstlane_b32 s6, v3
	buffer_inv sc1
	s_add_u32 s8, s34, 0x3500
	s_addc_u32 s9, s35, 0
	v_rcp_iflag_f32_e32 v4, v4
	v_add_u32_e32 v2, s6, v2
	v_add_u32_e32 v5, 1, v2
	s_mov_b64 s[22:23], -1
	v_mul_f32_e32 v3, 0x4f7ffffe, v4
	v_cvt_u32_f32_e32 v3, v3
	v_sub_u32_e32 v4, 0, v1
	v_mul_lo_u32 v4, v4, v3
	v_mul_hi_u32 v4, v3, v4
	v_add_u32_e32 v3, v3, v4
	v_mul_hi_u32 v3, v2, v3
	v_mul_lo_u32 v4, v3, v1
	v_sub_u32_e32 v2, v2, v4
	v_add_u32_e32 v6, 1, v3
	v_cmp_ge_u32_e32 vcc, v2, v1
	v_sub_u32_e32 v4, v2, v1
	s_nop 0
	v_cndmask_b32_e32 v3, v3, v6, vcc
	v_cndmask_b32_e32 v2, v2, v4, vcc
	v_add_u32_e32 v4, 1, v3
	v_cmp_ge_u32_e32 vcc, v2, v1
	s_nop 1
	v_cndmask_b32_e32 v4, v3, v4, vcc
	v_mul_lo_u32 v2, v1, v4
	v_add_u32_e32 v1, v2, v1
	v_cmp_ne_u32_e32 vcc, v5, v1
	v_mov_b64_e32 v[2:3], s[8:9]
	s_and_saveexec_b64 s[6:7], vcc
	s_cbranch_execz .LBB0_504
	v_mov_b32_e32 v1, 0
	global_load_dword v2, v1, s[8:9] sc1
	s_mov_b64 s[26:27], 0
	s_waitcnt vmcnt(0)
	v_cmp_eq_u32_e32 vcc, v2, v4
	s_and_saveexec_b64 s[24:25], vcc
	s_cbranch_execz .LBB0_503
	s_add_u32 s22, s34, 0x200
	s_addc_u32 s23, s35, 0
	s_mov_b32 s11, 1
	s_branch .LBB0_496

; __device__ __forceinline__ unsigned xb_ld(unsigned* p)              { return __hip_atomic_load(p, __ATOMIC_RELAXED, __HIP_MEMORY_SCOPE_AGENT); }
; __device__ __forceinline__ unsigned xb_add(unsigned* p, unsigned v) { return __hip_atomic_fetch_add(p, v, __ATOMIC_RELAXED, __HIP_MEMORY_SCOPE_AGENT); }
; #define XB_SPIN(cond, bar) do { unsigned _sp = 0; while (cond) { __builtin_amdgcn_s_sleep(1); \
;     if ((++_sp & 255u) == 0u) { if (xb_ld(&(bar)[XB_TMO])) break; if (_sp > XB_SPIN_CAP) { atomicAdd(&(bar)[XB_TMO], 1u); break; } } } } while (0)
; __device__ __forceinline__ void xcd_barrier(const XcdBarrier& b) {
;     ...
;         const unsigned old = xb_add(&bar[XB_XSUB(b.x)], 1u);
;         const unsigned gen = old / nloc;
;         if (old + 1u == (gen + 1u) * nloc) {
;             __builtin_amdgcn_fence(__ATOMIC_RELEASE, "agent");
;             asm volatile("s_waitcnt vmcnt(0)" ::: "memory");
;             const unsigned og = xb_add(&bar[XB_TOP], 1u);
;             const unsigned tg = og / nx;
;             if (og + 1u == (tg + 1u) * nx) xb_add(&bar[XB_TOPGEN], 1u);
;             else XB_SPIN(xb_ld(&bar[XB_TOPGEN]) == tg, bar);
;             __builtin_amdgcn_fence(__ATOMIC_ACQUIRE, "agent");
;             xb_add(&bar[XB_XGEN(b.x)], 1u);
;             asm volatile("s_waitcnt vmcnt(0)" ::: "memory");
;         } else {
;             XB_SPIN(xb_ld(&bar[XB_XGEN(b.x)]) == gen, bar);
.LBB0_580:
	s_or_b64 exec, exec, s[6:7]
	v_cvt_f32_u32_e32 v5, v3
	s_waitcnt vmcnt(0)
	v_readfirstlane_b32 s4, v4
	v_sub_u32_e32 v4, 0, v3
	v_rcp_iflag_f32_e32 v5, v5
	v_add_u32_e32 v6, s4, v2
	v_mul_f32_e32 v5, 0x4f7ffffe, v5
	v_cvt_u32_f32_e32 v5, v5
	v_mul_lo_u32 v2, v4, v5
	v_mul_hi_u32 v2, v5, v2
	v_add_u32_e32 v2, v5, v2
	v_mul_hi_u32 v2, v6, v2
	v_mul_lo_u32 v4, v2, v3
	v_sub_u32_e32 v4, v6, v4
	v_add_u32_e32 v5, 1, v2
	v_cmp_ge_u32_e32 vcc, v4, v3
	s_nop 1
	v_cndmask_b32_e32 v2, v2, v5, vcc
	v_sub_u32_e32 v5, v4, v3
	v_cndmask_b32_e32 v4, v4, v5, vcc
	v_add_u32_e32 v5, 1, v2
	v_cmp_ge_u32_e32 vcc, v4, v3
	v_add_u32_e32 v4, 1, v6
	s_nop 0
	v_cndmask_b32_e32 v2, v2, v5, vcc
	v_mul_lo_u32 v5, v3, v2
	v_add_u32_e32 v3, v5, v3
	v_cmp_ne_u32_e32 vcc, v4, v3
	s_and_saveexec_b64 s[4:5], vcc
	s_xor_b64 s[4:5], exec, s[4:5]
	s_cbranch_execz .LBB0_594
	s_waitcnt lgkmcnt(0)
	buffer_inv sc1
	v_mov_b32_e32 v1, 0x2000
	global_load_dword v1, v1, s[2:3] offset:1024 sc1
	s_add_u32 s8, s2, 0x2400
	s_addc_u32 s9, s3, 0
	s_waitcnt vmcnt(0)
	v_cmp_eq_u32_e32 vcc, v1, v2
	s_and_saveexec_b64 s[6:7], vcc
	s_cbranch_execz .LBB0_593
	s_mov_b32 s11, 1
	s_mov_b64 s[20:21], 0
	v_mov_b32_e32 v1, 0
	s_branch .LBB0_584

; __device__ __forceinline__ unsigned xb_ld(unsigned* p)              { return __hip_atomic_load(p, __ATOMIC_RELAXED, __HIP_MEMORY_SCOPE_AGENT); }
; __device__ __forceinline__ unsigned xb_add(unsigned* p, unsigned v) { return __hip_atomic_fetch_add(p, v, __ATOMIC_RELAXED, __HIP_MEMORY_SCOPE_AGENT); }
; #define XB_SPIN(cond, bar) do { unsigned _sp = 0; while (cond) { __builtin_amdgcn_s_sleep(1); \
;     if ((++_sp & 255u) == 0u) { if (xb_ld(&(bar)[XB_TMO])) break; if (_sp > XB_SPIN_CAP) { atomicAdd(&(bar)[XB_TMO], 1u); break; } } } } while (0)
; __device__ __forceinline__ void xcd_barrier(const XcdBarrier& b) {
;     ...
;             const unsigned og = xb_add(&bar[XB_TOP], 1u);
;             const unsigned tg = og / nx;
;             if (og + 1u == (tg + 1u) * nx) xb_add(&bar[XB_TOPGEN], 1u);
;             else XB_SPIN(xb_ld(&bar[XB_TOPGEN]) == tg, bar);
.LBB0_597:
	s_or_b64 exec, exec, s[8:9]
	v_cvt_f32_u32_e32 v4, v1
	s_waitcnt vmcnt(0)
	v_readfirstlane_b32 s6, v3
	buffer_inv sc1
	s_add_u32 s8, s34, 0x3500
	s_addc_u32 s9, s35, 0
	v_rcp_iflag_f32_e32 v4, v4
	v_add_u32_e32 v2, s6, v2
	v_add_u32_e32 v5, 1, v2
	s_mov_b64 s[20:21], -1
	v_mul_f32_e32 v3, 0x4f7ffffe, v4
	v_cvt_u32_f32_e32 v3, v3
	v_sub_u32_e32 v4, 0, v1
	v_mul_lo_u32 v4, v4, v3
	v_mul_hi_u32 v4, v3, v4
	v_add_u32_e32 v3, v3, v4
	v_mul_hi_u32 v3, v2, v3
	v_mul_lo_u32 v4, v3, v1
	v_sub_u32_e32 v2, v2, v4
	v_add_u32_e32 v6, 1, v3
	v_cmp_ge_u32_e32 vcc, v2, v1
	v_sub_u32_e32 v4, v2, v1
	s_nop 0
	v_cndmask_b32_e32 v3, v3, v6, vcc
	v_cndmask_b32_e32 v2, v2, v4, vcc
	v_add_u32_e32 v4, 1, v3
	v_cmp_ge_u32_e32 vcc, v2, v1
	s_nop 1
	v_cndmask_b32_e32 v4, v3, v4, vcc
	v_mul_lo_u32 v2, v1, v4
	v_add_u32_e32 v1, v2, v1
	v_cmp_ne_u32_e32 vcc, v5, v1
	v_mov_b64_e32 v[2:3], s[8:9]
	s_and_saveexec_b64 s[6:7], vcc
	s_cbranch_execz .LBB0_609
	v_mov_b32_e32 v1, 0
	global_load_dword v2, v1, s[8:9] sc1
	s_mov_b64 s[26:27], 0
	s_waitcnt vmcnt(0)
	v_cmp_eq_u32_e32 vcc, v2, v4
	s_and_saveexec_b64 s[24:25], vcc
	s_cbranch_execz .LBB0_608
	s_add_u32 s20, s34, 0x200
	s_addc_u32 s21, s35, 0
	s_mov_b32 s11, 1
	s_branch .LBB0_601

; __device__ __forceinline__ unsigned xb_ld(unsigned* p)              { return __hip_atomic_load(p, __ATOMIC_RELAXED, __HIP_MEMORY_SCOPE_AGENT); }
; __device__ __forceinline__ unsigned xb_add(unsigned* p, unsigned v) { return __hip_atomic_fetch_add(p, v, __ATOMIC_RELAXED, __HIP_MEMORY_SCOPE_AGENT); }
; #define XB_SPIN(cond, bar) do { unsigned _sp = 0; while (cond) { __builtin_amdgcn_s_sleep(1); \
;     if ((++_sp & 255u) == 0u) { if (xb_ld(&(bar)[XB_TMO])) break; if (_sp > XB_SPIN_CAP) { atomicAdd(&(bar)[XB_TMO], 1u); break; } } } } while (0)
; __device__ __forceinline__ void xcd_barrier(const XcdBarrier& b) {
;     ...
;         const unsigned old = xb_add(&bar[XB_XSUB(b.x)], 1u);
;         const unsigned gen = old / nloc;
;         if (old + 1u == (gen + 1u) * nloc) {
;             __builtin_amdgcn_fence(__ATOMIC_RELEASE, "agent");
;             asm volatile("s_waitcnt vmcnt(0)" ::: "memory");
;             const unsigned og = xb_add(&bar[XB_TOP], 1u);
;             const unsigned tg = og / nx;
;             if (og + 1u == (tg + 1u) * nx) xb_add(&bar[XB_TOPGEN], 1u);
;             else XB_SPIN(xb_ld(&bar[XB_TOPGEN]) == tg, bar);
;             __builtin_amdgcn_fence(__ATOMIC_ACQUIRE, "agent");
;             xb_add(&bar[XB_XGEN(b.x)], 1u);
;             asm volatile("s_waitcnt vmcnt(0)" ::: "memory");
;         } else {
;             XB_SPIN(xb_ld(&bar[XB_XGEN(b.x)]) == gen, bar);
.LBB0_656:
	s_or_b64 exec, exec, s[6:7]
	v_cvt_f32_u32_e32 v5, v3
	s_waitcnt vmcnt(0)
	v_readfirstlane_b32 s4, v4
	v_sub_u32_e32 v4, 0, v3
	v_rcp_iflag_f32_e32 v5, v5
	v_add_u32_e32 v6, s4, v2
	v_mul_f32_e32 v5, 0x4f7ffffe, v5
	v_cvt_u32_f32_e32 v5, v5
	v_mul_lo_u32 v2, v4, v5
	v_mul_hi_u32 v2, v5, v2
	v_add_u32_e32 v2, v5, v2
	v_mul_hi_u32 v2, v6, v2
	v_mul_lo_u32 v4, v2, v3
	v_sub_u32_e32 v4, v6, v4
	v_add_u32_e32 v5, 1, v2
	v_cmp_ge_u32_e32 vcc, v4, v3
	s_nop 1
	v_cndmask_b32_e32 v2, v2, v5, vcc
	v_sub_u32_e32 v5, v4, v3
	v_cndmask_b32_e32 v4, v4, v5, vcc
	v_add_u32_e32 v5, 1, v2
	v_cmp_ge_u32_e32 vcc, v4, v3
	v_add_u32_e32 v4, 1, v6
	s_nop 0
	v_cndmask_b32_e32 v2, v2, v5, vcc
	v_mul_lo_u32 v5, v3, v2
	v_add_u32_e32 v3, v5, v3
	v_cmp_ne_u32_e32 vcc, v4, v3
	s_and_saveexec_b64 s[4:5], vcc
	s_xor_b64 s[4:5], exec, s[4:5]
	s_cbranch_execz .LBB0_670
	s_waitcnt lgkmcnt(0)
	buffer_inv sc1
	v_mov_b32_e32 v1, 0x2000
	global_load_dword v1, v1, s[2:3] offset:1024 sc1
	s_add_u32 s8, s2, 0x2400
	s_addc_u32 s9, s3, 0
	s_waitcnt vmcnt(0)
	v_cmp_eq_u32_e32 vcc, v1, v2
	s_and_saveexec_b64 s[6:7], vcc
	s_cbranch_execz .LBB0_669
	s_mov_b32 s11, 1
	s_mov_b64 s[14:15], 0
	v_mov_b32_e32 v1, 0
	s_branch .LBB0_660

; __device__ __forceinline__ unsigned xb_ld(unsigned* p)              { return __hip_atomic_load(p, __ATOMIC_RELAXED, __HIP_MEMORY_SCOPE_AGENT); }
; __device__ __forceinline__ unsigned xb_add(unsigned* p, unsigned v) { return __hip_atomic_fetch_add(p, v, __ATOMIC_RELAXED, __HIP_MEMORY_SCOPE_AGENT); }
; #define XB_SPIN(cond, bar) do { unsigned _sp = 0; while (cond) { __builtin_amdgcn_s_sleep(1); \
;     if ((++_sp & 255u) == 0u) { if (xb_ld(&(bar)[XB_TMO])) break; if (_sp > XB_SPIN_CAP) { atomicAdd(&(bar)[XB_TMO], 1u); break; } } } } while (0)
; __device__ __forceinline__ void xcd_barrier(const XcdBarrier& b) {
;     ...
;             const unsigned og = xb_add(&bar[XB_TOP], 1u);
;             const unsigned tg = og / nx;
;             if (og + 1u == (tg + 1u) * nx) xb_add(&bar[XB_TOPGEN], 1u);
;             else XB_SPIN(xb_ld(&bar[XB_TOPGEN]) == tg, bar);
.LBB0_673:
	s_or_b64 exec, exec, s[6:7]
	v_cvt_f32_u32_e32 v4, v1
	s_waitcnt vmcnt(0)
	v_readfirstlane_b32 s4, v3
	buffer_inv sc1
	s_add_u32 s6, s34, 0x3500
	s_addc_u32 s7, s35, 0
	v_rcp_iflag_f32_e32 v4, v4
	v_add_u32_e32 v2, s4, v2
	v_add_u32_e32 v5, 1, v2
	s_mov_b64 s[8:9], -1
	v_mul_f32_e32 v3, 0x4f7ffffe, v4
	v_cvt_u32_f32_e32 v3, v3
	v_sub_u32_e32 v4, 0, v1
	v_mul_lo_u32 v4, v4, v3
	v_mul_hi_u32 v4, v3, v4
	v_add_u32_e32 v3, v3, v4
	v_mul_hi_u32 v3, v2, v3
	v_mul_lo_u32 v4, v3, v1
	v_sub_u32_e32 v2, v2, v4
	v_add_u32_e32 v6, 1, v3
	v_cmp_ge_u32_e32 vcc, v2, v1
	v_sub_u32_e32 v4, v2, v1
	s_nop 0
	v_cndmask_b32_e32 v3, v3, v6, vcc
	v_cndmask_b32_e32 v2, v2, v4, vcc
	v_add_u32_e32 v4, 1, v3
	v_cmp_ge_u32_e32 vcc, v2, v1
	s_nop 1
	v_cndmask_b32_e32 v4, v3, v4, vcc
	v_mul_lo_u32 v2, v1, v4
	v_add_u32_e32 v1, v2, v1
	v_cmp_ne_u32_e32 vcc, v5, v1
	v_mov_b64_e32 v[2:3], s[6:7]
	s_and_saveexec_b64 s[4:5], vcc
	s_cbranch_execz .LBB0_685
	v_mov_b32_e32 v1, 0
	global_load_dword v2, v1, s[6:7] sc1
	s_mov_b64 s[20:21], 0
	s_waitcnt vmcnt(0)
	v_cmp_eq_u32_e32 vcc, v2, v4
	s_and_saveexec_b64 s[14:15], vcc
	s_cbranch_execz .LBB0_684
	s_add_u32 s8, s34, 0x200
	s_addc_u32 s9, s35, 0
	s_mov_b32 s11, 1
	s_branch .LBB0_677

; __device__ __forceinline__ unsigned xb_ld(unsigned* p)              { return __hip_atomic_load(p, __ATOMIC_RELAXED, __HIP_MEMORY_SCOPE_AGENT); }
; __device__ __forceinline__ unsigned xb_add(unsigned* p, unsigned v) { return __hip_atomic_fetch_add(p, v, __ATOMIC_RELAXED, __HIP_MEMORY_SCOPE_AGENT); }
; #define XB_SPIN(cond, bar) do { unsigned _sp = 0; while (cond) { __builtin_amdgcn_s_sleep(1); \
;     if ((++_sp & 255u) == 0u) { if (xb_ld(&(bar)[XB_TMO])) break; if (_sp > XB_SPIN_CAP) { atomicAdd(&(bar)[XB_TMO], 1u); break; } } } } while (0)
; __device__ __forceinline__ void xcd_barrier(const XcdBarrier& b) {
;     ...
;             else XB_SPIN(xb_ld(&bar[XB_TOPGEN]) == tg, bar);
;             __builtin_amdgcn_fence(__ATOMIC_ACQUIRE, "agent");
;             xb_add(&bar[XB_XGEN(b.x)], 1u);
;             asm volatile("s_waitcnt vmcnt(0)" ::: "memory");
.LBB0_687:
	s_or_b64 exec, exec, s[4:5]
	s_mov_b64 s[4:5], exec
	v_mbcnt_lo_u32_b32 v1, s4, 0
	v_mbcnt_hi_u32_b32 v1, s5, v1
	v_cmp_eq_u32_e32 vcc, 0, v1
	s_and_saveexec_b64 s[6:7], vcc
	s_cbranch_execz .LBB0_689
	s_bcnt1_i32_b64 s4, s[4:5]
	v_mov_b32_e32 v1, 0x2000
	v_mov_b32_e32 v2, s4
	global_atomic_add v1, v2, s[2:3] offset:1024
